# v63 plus: the full vmcnt(0) in front of the first LRU pass-1 chunk's conv loads is dropped (the counted waits that follow retire the older gate-weight loads first), so the two load batches overlap
# baseline (speedup 1.0000x reference)
; #define LAS __attribute__((address_space(3)))
; template <int PASS>
; __device__ __forceinline__ void lru_unit(const LruP& P, const LruInv& V, int b, int c, LAS unsigned char* wl, LAS float* red, int wave, int lane, int pairpos) {
;     const int blk = wave, fr = lane & 15, fq = lane >> 4;
;     const size_t row0 = (size_t)b * SEQ + (size_t)c * 64;
;     LAS bf16* xc = (LAS bf16*)wl;
;     {
;         const int cg8 = lane & 7, tg = lane >> 3, ch0 = blk * 64 + cg8 * 8;
;         float cw[4][8], cb[8];
; #pragma unroll
;         for (int i = 0; i < 4; ++i) { const f32x4 a = *(const f32x4*)(P.conv_w + i * 512 + ch0), bq = *(const f32x4*)(P.conv_w + i * 512 + ch0 + 4);
;             cw[i][0] = a[0]; cw[i][1] = a[1]; cw[i][2] = a[2]; cw[i][3] = a[3]; cw[i][4] = bq[0]; cw[i][5] = bq[1]; cw[i][6] = bq[2]; cw[i][7] = bq[3]; }
;         { const f32x4 a = *(const f32x4*)(P.conv_b + ch0), bq = *(const f32x4*)(P.conv_b + ch0 + 4);
;             cb[0] = a[0]; cb[1] = a[1]; cb[2] = a[2]; cb[3] = a[3]; cb[4] = bq[0]; cb[5] = bq[1]; cb[6] = bq[2]; cb[7] = bq[3]; }
;         const int s0 = c * 64 + tg * 8;
;         const bf16* src = P.U + ((size_t)b * SEQ + s0) * NU + ch0;
;         float w0[8], w1[8], w2[8];
;         auto ldrow = [&](int ds, float* o) { const bool okr = (s0 + ds >= 0); v4u r = *(const v4u*)(src + (ptrdiff_t)(okr ? ds : 0) * NU); if (!okr) r = (v4u){0u, 0u, 0u, 0u};
;             o[0] = bflo(r.x); o[1] = bfhi(r.x); o[2] = bflo(r.y); o[3] = bfhi(r.y); o[4] = bflo(r.z); o[5] = bfhi(r.z); o[6] = bflo(r.w); o[7] = bfhi(r.w); };
;         ldrow(-3, w0); ldrow(-2, w1); ldrow(-1, w2);
; #pragma unroll
;         for (int t = 0; t < 8; ++t) { float cur[8], y[8]; ldrow(t, cur);
; #pragma unroll
;             for (int k = 0; k < 8; ++k) { y[k] = cb[k] + cw[0][k] * w0[k] + cw[1][k] * w1[k] + cw[2][k] * w2[k] + cw[3][k] * cur[k]; w0[k] = w1[k]; w1[k] = w2[k]; w2[k] = cur[k]; }
.LBB0_333:
	s_ashr_i32 s0, s14, 31
	s_lshr_b32 s0, s0, 26
	s_add_i32 s0, s14, s0
	s_ashr_i32 s16, s0, 6
	s_andn2_b32 s0, s0, 63
	s_sub_i32 s10, s14, s0
	s_ashr_i32 s17, s16, 31
	s_lshl_b32 s18, s10, 1
	v_lshl_or_b32 v116, s10, 7, v194
	s_lshl_b64 s[0:1], s[16:17], 25
	v_ashrrev_i32_e32 v117, 31, v116
	s_add_u32 s8, s38, s0
	s_addc_u32 s9, s39, s1
	v_lshlrev_b64 v[118:119], 12, v[116:117]
	v_lshl_add_u64 v[118:119], s[8:9], 0, v[118:119]
	v_cmp_lt_i32_e64 s[0:1], 2, v116
	v_lshl_add_u64 v[144:145], v[166:167], 1, v[118:119]
	v_cmp_lt_i32_e64 s[4:5], 1, v116
	v_cndmask_b32_e64 v119, 0, -1, s[0:1]
	v_cndmask_b32_e64 v118, 0, v197, s[0:1]
	v_lshl_add_u64 v[118:119], v[144:145], 0, v[118:119]
	global_load_dwordx4 v[146:149], v[168:169], off
	global_load_dwordx4 v[120:123], v[168:169], off offset:2048
	global_load_dwordx4 v[150:153], v[170:171], off
	global_load_dwordx4 v[112:115], v[176:177], off
	global_load_dwordx4 v[154:157], v[118:119], off
	v_cndmask_b32_e64 v119, 0, -1, s[4:5]
	v_cndmask_b32_e64 v118, 0, v198, s[4:5]
	v_lshl_add_u64 v[118:119], v[144:145], 0, v[118:119]
	global_load_dwordx4 v[158:161], v[118:119], off
	v_cmp_lt_i32_e64 s[6:7], 0, v116
	s_cmp_gt_i32 s10, -1
	s_mov_b32 s43, s11
	v_cndmask_b32_e64 v116, 0, -1, s[6:7]
	v_mov_b32_e32 v117, v116
	v_lshlrev_b64 v[116:117], 12, v[116:117]
	v_lshl_add_u64 v[116:117], v[144:145], 0, v[116:117]
	global_load_dwordx4 v[180:183], v[116:117], off
	global_load_dwordx4 v[184:187], v[144:145], off
	global_load_dwordx4 v[128:131], v[178:179], off
	global_load_dwordx4 v[188:191], v[168:169], off offset:16
	global_load_dwordx4 v[132:135], v[168:169], off offset:2064
	global_load_dwordx4 v[124:127], v[178:179], off offset:16
	global_load_dwordx4 v[202:205], v[170:171], off offset:16
	global_load_dwordx4 v[116:119], v[176:177], off offset:16
	s_mov_b32 s49, s11
	s_mov_b32 s53, s11
	s_mov_b32 s59, s11
	s_mov_b32 s57, s11
	s_mov_b32 s45, s11
	s_waitcnt vmcnt(13)
	v_mov_b32_e32 v140, v146
	s_waitcnt vmcnt(12)
	v_mov_b32_e32 v143, v122
	v_mov_b32_e32 v141, v120
	v_mov_b32_e32 v120, v147
	s_waitcnt vmcnt(9)
	v_cndmask_b32_e64 v122, 0, v154, s[0:1]
	v_mov_b32_e32 v142, v148
	v_lshlrev_b32_e32 v208, 16, v122
	v_and_b32_e32 v210, 0xffff0000, v122
	s_waitcnt vmcnt(8)
	v_cndmask_b32_e64 v146, 0, v158, s[4:5]
	v_cndmask_b32_e64 v193, 0, v161, s[4:5]
	v_cndmask_b32_e64 v220, 0, v160, s[4:5]
	v_cndmask_b32_e64 v148, 0, v159, s[4:5]
	s_waitcnt vmcnt(7)
	v_cndmask_b32_e64 v147, 0, v180, s[6:7]
	s_cselect_b64 s[4:5], -1, 0
	v_lshlrev_b32_e32 v209, 16, v146
	v_and_b32_e32 v211, 0xffff0000, v146
	v_mov_b32_e32 v136, v150
	v_mov_b32_e32 v138, v152
	v_mov_b32_e32 v139, v114
	v_cndmask_b32_e64 v152, 0, v156, s[0:1]
	v_cndmask_b32_e64 v114, 0, v155, s[0:1]
	s_waitcnt vmcnt(6)
	v_cndmask_b32_e64 v150, 0, v184, s[4:5]
	v_lshlrev_b32_e32 v154, 16, v147
	v_and_b32_e32 v156, 0xffff0000, v147
	v_pk_mul_f32 v[146:147], v[140:141], v[208:209]
	v_pk_mul_f32 v[160:161], v[120:121], v[210:211]
	v_mov_b32_e32 v137, v112
	v_mov_b32_e32 v112, v151
	v_cndmask_b32_e64 v192, 0, v157, s[0:1]
	v_and_b32_e32 v157, 0xffff0000, v150
	v_lshlrev_b32_e32 v213, 16, v148
	v_lshlrev_b32_e32 v212, 16, v114
	s_waitcnt vmcnt(5)
	v_add_f32_e32 v122, v128, v146
	v_add_f32_e32 v146, v129, v160
	v_cndmask_b32_e64 v216, 0, v181, s[6:7]
	v_cndmask_b32_e64 v185, 0, v185, s[4:5]
	v_lshlrev_b32_e32 v155, 16, v150
	v_pk_mul_f32 v[162:163], v[112:113], v[156:157]
	v_pk_mul_f32 v[180:181], v[142:143], v[212:213]
	v_add_f32_e32 v146, v146, v161
	v_lshlrev_b32_e32 v158, 16, v216
	v_lshlrev_b32_e32 v159, 16, v185
	v_pk_mul_f32 v[150:151], v[136:137], v[154:155]
	v_add_f32_e32 v160, v130, v180
	v_add_f32_e32 v122, v122, v147
	v_add_f32_e32 v146, v146, v162
	v_add_f32_e32 v160, v160, v181
	v_add_f32_e32 v122, v122, v150
	v_add_f32_e32 v163, v146, v163
	v_pk_mul_f32 v[146:147], v[138:139], v[158:159]
	v_add_f32_e32 v162, v122, v151
	v_add_f32_e32 v122, v160, v146
	v_add_f32_e32 v180, v122, v147
	v_and_b32_e32 v215, 0xffff0000, v148
	v_and_b32_e32 v214, 0xffff0000, v114
	v_mov_b32_e32 v122, v149
	v_pk_mul_f32 v[146:147], v[122:123], v[214:215]
	v_cndmask_b32_e64 v228, 0, v187, s[4:5]
	v_add_f32_e32 v114, v131, v146
	v_cndmask_b32_e64 v222, 0, v186, s[4:5]
	v_add_f32_e32 v148, v114, v147
	v_and_b32_e32 v187, 0xffff0000, v185
	v_and_b32_e32 v186, 0xffff0000, v216
	v_mov_b32_e32 v114, v153
	v_pk_mul_f32 v[146:147], v[114:115], v[186:187]
	v_lshlrev_b32_e32 v217, 16, v220
	v_add_f32_e32 v146, v148, v146
	v_lshlrev_b32_e32 v216, 16, v152
	s_waitcnt vmcnt(4)
	v_mov_b32_e32 v150, v188
	s_waitcnt vmcnt(3)
	v_mov_b32_e32 v151, v132
	v_add_f32_e32 v181, v146, v147
	v_pk_mul_f32 v[146:147], v[150:151], v[216:217]
	v_cndmask_b32_e64 v182, 0, v182, s[6:7]
	s_waitcnt vmcnt(2)
	v_add_f32_e32 v132, v124, v146
	v_add_f32_e32 v132, v132, v147
	v_lshlrev_b32_e32 v218, 16, v182
	v_lshlrev_b32_e32 v219, 16, v222
	s_waitcnt vmcnt(1)
	v_mov_b32_e32 v146, v202
	s_waitcnt vmcnt(0)
; #define LAS __attribute__((address_space(3)))
; __device__ __forceinline__ unsigned pk2(float lo, float hi) { return pg8::cvt_pk_bf16(lo, hi); }
; template <int PASS>
; __device__ __forceinline__ void lru_unit(const LruP& P, const LruInv& V, int b, int c, LAS unsigned char* wl, LAS float* red, int wave, int lane, int pairpos) {
;     ...
;         auto ldrow = [&](int ds, float* o) { const bool okr = (s0 + ds >= 0); v4u r = *(const v4u*)(src + (ptrdiff_t)(okr ? ds : 0) * NU); if (!okr) r = (v4u){0u, 0u, 0u, 0u};
;             o[0] = bflo(r.x); o[1] = bfhi(r.x); o[2] = bflo(r.y); o[3] = bfhi(r.y); o[4] = bflo(r.z); o[5] = bfhi(r.z); o[6] = bflo(r.w); o[7] = bfhi(r.w); };
;         ldrow(-3, w0); ldrow(-2, w1); ldrow(-1, w2);
; #pragma unroll
;         for (int t = 0; t < 8; ++t) { float cur[8], y[8]; ldrow(t, cur);
; #pragma unroll
;             for (int k = 0; k < 8; ++k) { y[k] = cb[k] + cw[0][k] * w0[k] + cw[1][k] * w1[k] + cw[2][k] * w2[k] + cw[3][k] * cur[k]; w0[k] = w1[k]; w1[k] = w2[k]; w2[k] = cur[k]; }
;             v4u o; o.x = pk2(y[0], y[1]); o.y = pk2(y[2], y[3]); o.z = pk2(y[4], y[5]); o.w = pk2(y[6], y[7]);
;             *(LAS v4u*)(xc + (tg * 8 + t) * 72 + cg8 * 8) = o; }
	v_mov_b32_e32 v147, v116
	v_pk_mul_f32 v[148:149], v[146:147], v[218:219]
	v_and_b32_e32 v221, 0xffff0000, v220
	v_add_f32_e32 v116, v132, v148
	v_and_b32_e32 v220, 0xffff0000, v152
	v_mov_b32_e32 v132, v189
	v_add_f32_e32 v184, v116, v149
	v_pk_mul_f32 v[148:149], v[132:133], v[220:221]
	v_and_b32_e32 v223, 0xffff0000, v222
	v_add_f32_e32 v116, v125, v148
	v_add_f32_e32 v152, v116, v149
	v_and_b32_e32 v222, 0xffff0000, v182
	v_mov_b32_e32 v116, v203
	v_pk_mul_f32 v[148:149], v[116:117], v[222:223]
	v_lshlrev_b32_e32 v203, 16, v193
	v_add_f32_e32 v148, v152, v148
	v_lshlrev_b32_e32 v202, 16, v192
	v_mov_b32_e32 v152, v190
	v_mov_b32_e32 v153, v134
	v_add_f32_e32 v182, v148, v149
	v_pk_mul_f32 v[148:149], v[152:153], v[202:203]
	v_cndmask_b32_e64 v183, 0, v183, s[6:7]
	v_add_f32_e32 v134, v126, v148
	v_add_f32_e32 v134, v134, v149
	v_lshlrev_b32_e32 v224, 16, v183
	v_lshlrev_b32_e32 v225, 16, v228
	v_mov_b32_e32 v148, v204
	v_mov_b32_e32 v149, v118
	v_pk_mul_f32 v[160:161], v[148:149], v[224:225]
	v_and_b32_e32 v227, 0xffff0000, v193
	v_add_f32_e32 v118, v134, v160
	v_and_b32_e32 v226, 0xffff0000, v192
	v_mov_b32_e32 v134, v191
	v_add_f32_e32 v185, v118, v161
	v_pk_mul_f32 v[160:161], v[134:135], v[226:227]
	v_and_b32_e32 v229, 0xffff0000, v228
	v_add_f32_e32 v118, v127, v160
	v_add_f32_e32 v188, v118, v161
	v_and_b32_e32 v228, 0xffff0000, v183
	v_mov_b32_e32 v118, v205
	v_pk_mul_f32 v[160:161], v[118:119], v[228:229]
	s_and_b64 s[0:1], s[4:5], exec
	v_add_f32_e32 v160, v188, v160
	s_cselect_b32 s10, 0x1000, 0
	v_add_f32_e32 v183, v160, v161
	v_cvt_pk_bf16_f32 v160, v162, v163
	v_cvt_pk_bf16_f32 v161, v180, v181
	v_lshl_add_u64 v[180:181], v[144:145], 0, s[10:11]
	v_cvt_pk_bf16_f32 v162, v184, v182
	v_cvt_pk_bf16_f32 v163, v185, v183
	global_load_dwordx4 v[180:183], v[180:181], off
	v_pk_mov_b32 v[204:205], v[208:209], v[154:155] op_sel:[1,0]
	ds_write_b128 v199, v[160:163]
	v_pk_mul_f32 v[204:205], v[140:141], v[204:205]
	v_pk_mov_b32 v[202:203], v[202:203], v[224:225] op_sel:[1,0]
	v_mov_b32_e32 v192, v225
	v_pk_mul_f32 v[202:203], v[152:153], v[202:203]
	v_mov_b32_e32 v190, v229
	v_add_f32_e32 v184, v126, v202
	v_add_f32_e32 v184, v184, v203
	v_pk_mov_b32 v[202:203], v[226:227], v[228:229] op_sel:[1,0]
	s_cselect_b32 s42, 0x2000, 0
	v_pk_mul_f32 v[202:203], v[134:135], v[202:203]
	v_lshl_add_u64 v[208:209], v[144:145], 0, s[42:43]
	v_add_f32_e32 v188, v127, v202
	v_add_f32_e32 v188, v188, v203
	s_cselect_b32 s48, 0x3000, 0
	s_cselect_b32 s52, 0x4000, 0
	s_cselect_b32 s58, 0x5000, 0
	s_cselect_b32 s56, 0x6000, 0
	s_cselect_b32 s44, 0x7000, 0
	s_lshl_b32 s15, s16, 7
	s_add_i32 s0, s15, s18
	s_ashr_i32 s1, s0, 31
	s_lshl_b64 s[16:17], s[0:1], 17
	s_mov_b32 s6, s11
	s_waitcnt vmcnt(0)
	v_cndmask_b32_e64 v160, 0, v183, s[4:5]
	v_lshlrev_b32_e32 v193, 16, v160
	v_and_b32_e32 v191, 0xffff0000, v160
	v_add_f32_e32 v160, v128, v204
	v_add_f32_e32 v160, v160, v205
	v_pk_mov_b32 v[204:205], v[210:211], v[156:157] op_sel:[1,0]
	v_cndmask_b32_e64 v162, 0, v182, s[4:5]
	v_pk_mul_f32 v[204:205], v[120:121], v[204:205]
	v_lshlrev_b32_e32 v189, 16, v162
	v_and_b32_e32 v185, 0xffff0000, v162
	v_add_f32_e32 v162, v129, v204
	v_add_f32_e32 v210, v162, v205
	v_pk_mov_b32 v[204:205], v[212:213], v[158:159] op_sel:[1,0]
	v_cndmask_b32_e64 v161, 0, v180, s[4:5]
	v_pk_mul_f32 v[204:205], v[142:143], v[204:205]
	v_pk_mul_f32 v[202:203], v[148:149], v[192:193]
	v_add_f32_e32 v162, v130, v204
	v_add_f32_e32 v162, v162, v205
	v_pk_mov_b32 v[204:205], v[214:215], v[186:187] op_sel:[1,0]
	v_add_f32_e32 v184, v184, v202
	v_pk_mul_f32 v[204:205], v[122:123], v[204:205]
	v_cndmask_b32_e64 v181, 0, v181, s[4:5]
	v_add_f32_e32 v180, v131, v204
	v_add_f32_e32 v211, v180, v205
	v_pk_mov_b32 v[204:205], v[216:217], v[218:219] op_sel:[1,0]
	v_lshlrev_b32_e32 v183, 16, v181
	v_pk_mul_f32 v[204:205], v[150:151], v[204:205]
	v_and_b32_e32 v181, 0xffff0000, v181
	v_add_f32_e32 v180, v124, v204
	v_add_f32_e32 v180, v180, v205
	v_pk_mov_b32 v[204:205], v[220:221], v[222:223] op_sel:[1,0]
	v_lshlrev_b32_e32 v163, 16, v161
	v_pk_mul_f32 v[204:205], v[132:133], v[204:205]
	v_and_b32_e32 v161, 0xffff0000, v161
	v_add_f32_e32 v182, v125, v204
	v_add_f32_e32 v182, v182, v205
	v_add_f32_e32 v205, v184, v203
	v_pk_mul_f32 v[202:203], v[118:119], v[190:191]
	v_mov_b32_e32 v220, v191
	v_add_f32_e32 v184, v188, v202
	v_mov_b32_e32 v188, v219
	v_add_f32_e32 v212, v184, v203
	v_pk_mul_f32 v[202:203], v[146:147], v[188:189]
	v_mov_b32_e32 v184, v223
	v_add_f32_e32 v180, v180, v202
	v_add_f32_e32 v204, v180, v203
	v_pk_mul_f32 v[202:203], v[116:117], v[184:185]
	v_pk_mul_f32 v[190:191], v[134:135], v[190:191]
	v_add_f32_e32 v180, v182, v202
	v_mov_b32_e32 v182, v159
	v_add_f32_e32 v213, v180, v203
	v_pk_mul_f32 v[202:203], v[138:139], v[182:183]
	v_mov_b32_e32 v180, v187
	v_add_f32_e32 v162, v162, v202
	v_add_f32_e32 v214, v162, v203
	v_pk_mul_f32 v[202:203], v[114:115], v[180:181]
	v_add_f32_e32 v190, v127, v190
	v_add_f32_e32 v162, v211, v202
	v_add_f32_e32 v211, v162, v203
	v_mov_b32_e32 v162, v155
	v_pk_mul_f32 v[202:203], v[136:137], v[162:163]
	v_pk_mul_f32 v[154:155], v[140:141], v[154:155]
	v_add_f32_e32 v160, v160, v202
	v_add_f32_e32 v215, v160, v203
	v_mov_b32_e32 v160, v157
	v_pk_mul_f32 v[202:203], v[112:113], v[160:161]
	v_add_f32_e32 v154, v128, v154
	v_add_f32_e32 v202, v210, v202
	v_add_f32_e32 v202, v202, v203
	v_cvt_pk_bf16_f32 v202, v215, v202
	v_cvt_pk_bf16_f32 v203, v214, v211
	v_cvt_pk_bf16_f32 v204, v204, v213
	v_cvt_pk_bf16_f32 v205, v205, v212
	global_load_dwordx4 v[208:211], v[208:209], off
	v_add_f32_e32 v226, v154, v155
	v_pk_mul_f32 v[154:155], v[120:121], v[156:157]
	ds_write_b128 v199, v[202:205] offset:144
	v_add_f32_e32 v154, v129, v154
	v_add_f32_e32 v156, v154, v155
	v_pk_mul_f32 v[154:155], v[142:143], v[158:159]
	v_lshl_add_u64 v[158:159], v[144:145], 0, s[48:49]
	v_add_f32_e32 v154, v130, v154
	v_add_f32_e32 v157, v154, v155
	v_pk_mul_f32 v[154:155], v[122:123], v[186:187]
	v_add_f32_e32 v190, v190, v191
	v_add_f32_e32 v154, v131, v154
	v_add_f32_e32 v186, v154, v155
	v_pk_mul_f32 v[154:155], v[150:151], v[218:219]
	v_mov_b32_e32 v218, v193
	v_add_f32_e32 v154, v124, v154
	v_add_f32_e32 v212, v154, v155
	v_pk_mul_f32 v[154:155], v[132:133], v[222:223]
	v_pk_mul_f32 v[192:193], v[152:153], v[192:193]
	v_add_f32_e32 v154, v125, v154
	v_add_f32_e32 v222, v154, v155
	v_pk_mul_f32 v[154:155], v[152:153], v[224:225]
	v_add_f32_e32 v192, v126, v192
	v_add_f32_e32 v154, v126, v154
	v_add_f32_e32 v214, v154, v155
	v_pk_mul_f32 v[154:155], v[134:135], v[228:229]
	s_waitcnt vmcnt(0)
; #define LAS __attribute__((address_space(3)))
; __device__ __forceinline__ unsigned pk2(float lo, float hi) { return pg8::cvt_pk_bf16(lo, hi); }
; template <int PASS>
; __device__ __forceinline__ void lru_unit(const LruP& P, const LruInv& V, int b, int c, LAS unsigned char* wl, LAS float* red, int wave, int lane, int pairpos) {
;     ...
;         auto ldrow = [&](int ds, float* o) { const bool okr = (s0 + ds >= 0); v4u r = *(const v4u*)(src + (ptrdiff_t)(okr ? ds : 0) * NU); if (!okr) r = (v4u){0u, 0u, 0u, 0u};
;             o[0] = bflo(r.x); o[1] = bfhi(r.x); o[2] = bflo(r.y); o[3] = bfhi(r.y); o[4] = bflo(r.z); o[5] = bfhi(r.z); o[6] = bflo(r.w); o[7] = bfhi(r.w); };
;         ldrow(-3, w0); ldrow(-2, w1); ldrow(-1, w2);
; #pragma unroll
;         for (int t = 0; t < 8; ++t) { float cur[8], y[8]; ldrow(t, cur);
; #pragma unroll
;             for (int k = 0; k < 8; ++k) { y[k] = cb[k] + cw[0][k] * w0[k] + cw[1][k] * w1[k] + cw[2][k] * w2[k] + cw[3][k] * cur[k]; w0[k] = w1[k]; w1[k] = w2[k]; w2[k] = cur[k]; }
;             v4u o; o.x = pk2(y[0], y[1]); o.y = pk2(y[2], y[3]); o.z = pk2(y[4], y[5]); o.w = pk2(y[6], y[7]);
;             *(LAS v4u*)(xc + (tg * 8 + t) * 72 + cg8 * 8) = o; }
	v_cndmask_b32_e64 v208, 0, v208, s[4:5]
	v_add_f32_e32 v154, v127, v154
	v_add_f32_e32 v216, v154, v155
	v_cndmask_b32_e64 v154, 0, v211, s[4:5]
	v_cndmask_b32_e64 v155, 0, v210, s[4:5]
	v_lshlrev_b32_e32 v219, 16, v154
	v_and_b32_e32 v215, 0xffff0000, v155
	v_lshlrev_b32_e32 v217, 16, v155
	v_and_b32_e32 v221, 0xffff0000, v154
	v_pk_mul_f32 v[154:155], v[148:149], v[218:219]
	v_cndmask_b32_e64 v210, 0, v209, s[4:5]
	v_add_f32_e32 v154, v214, v154
	v_add_f32_e32 v202, v154, v155
	v_pk_mul_f32 v[154:155], v[118:119], v[220:221]
	v_mov_b32_e32 v214, v185
	v_add_f32_e32 v154, v216, v154
	v_mov_b32_e32 v216, v189
	v_add_f32_e32 v203, v154, v155
	v_pk_mul_f32 v[154:155], v[146:147], v[216:217]
	v_lshlrev_b32_e32 v213, 16, v210
	v_add_f32_e32 v154, v212, v154
	v_add_f32_e32 v204, v154, v155
	v_pk_mul_f32 v[154:155], v[116:117], v[214:215]
	v_mov_b32_e32 v212, v183
	v_add_f32_e32 v154, v222, v154
	v_add_f32_e32 v205, v154, v155
	v_pk_mul_f32 v[154:155], v[138:139], v[212:213]
	v_and_b32_e32 v211, 0xffff0000, v210
	v_add_f32_e32 v154, v157, v154
	v_mov_b32_e32 v210, v181
	v_add_f32_e32 v157, v154, v155
	v_pk_mul_f32 v[154:155], v[114:115], v[210:211]
	v_and_b32_e32 v187, 0xffff0000, v208
	v_lshlrev_b32_e32 v209, 16, v208
	v_add_f32_e32 v154, v186, v154
	v_mov_b32_e32 v208, v163
	v_add_f32_e32 v222, v154, v155
	v_pk_mul_f32 v[154:155], v[136:137], v[208:209]
	v_mov_b32_e32 v186, v161
	v_add_f32_e32 v154, v226, v154
	v_add_f32_e32 v223, v154, v155
	v_pk_mul_f32 v[154:155], v[112:113], v[186:187]
	v_pk_mul_f32 v[160:161], v[120:121], v[160:161]
	v_add_f32_e32 v154, v156, v154
	v_add_f32_e32 v154, v154, v155
	v_cvt_pk_bf16_f32 v154, v223, v154
	v_cvt_pk_bf16_f32 v155, v157, v222
	v_cvt_pk_bf16_f32 v156, v204, v205
	v_cvt_pk_bf16_f32 v157, v202, v203
	global_load_dwordx4 v[202:205], v[158:159], off
	v_add_f32_e32 v160, v129, v160
	v_add_f32_e32 v160, v160, v161
	v_add_f32_e32 v222, v192, v193
	v_pk_mul_f32 v[184:185], v[132:133], v[184:185]
	v_pk_mul_f32 v[180:181], v[122:123], v[180:181]
	v_mov_b32_e32 v192, v219
	v_add_f32_e32 v184, v125, v184
	v_add_f32_e32 v180, v131, v180
	ds_write_b128 v199, v[154:157] offset:288
	v_pk_mul_f32 v[188:189], v[150:151], v[188:189]
	v_add_f32_e32 v184, v184, v185
	v_add_f32_e32 v180, v180, v181
	v_add_f32_e32 v188, v124, v188
	v_add_f32_e32 v188, v188, v189
	v_pk_mul_f32 v[182:183], v[142:143], v[182:183]
	v_pk_mul_f32 v[162:163], v[140:141], v[162:163]
	v_add_f32_e32 v182, v130, v182
	v_add_f32_e32 v182, v182, v183
	v_add_f32_e32 v162, v128, v162
	v_add_f32_e32 v162, v162, v163
	v_lshl_add_u64 v[158:159], v[144:145], 0, s[52:53]
	v_pk_mul_f32 v[218:219], v[152:153], v[218:219]
	s_waitcnt vmcnt(0)
	v_cndmask_b32_e64 v161, 0, v205, s[4:5]
	v_lshlrev_b32_e32 v193, 16, v161
	v_pk_mul_f32 v[154:155], v[148:149], v[192:193]
	v_cndmask_b32_e64 v185, 0, v203, s[4:5]
	v_cndmask_b32_e64 v181, 0, v202, s[4:5]
	v_and_b32_e32 v203, 0xffff0000, v161
	v_add_f32_e32 v154, v222, v154
	v_mov_b32_e32 v202, v221
	v_cndmask_b32_e64 v191, 0, v204, s[4:5]
	v_add_f32_e32 v157, v154, v155
	v_pk_mul_f32 v[154:155], v[118:119], v[202:203]
	v_and_b32_e32 v189, 0xffff0000, v191
	v_lshlrev_b32_e32 v191, 16, v191
	v_add_f32_e32 v154, v190, v154
	v_mov_b32_e32 v190, v217
	v_add_f32_e32 v161, v154, v155
	v_pk_mul_f32 v[154:155], v[146:147], v[190:191]
	v_and_b32_e32 v183, 0xffff0000, v185
	v_add_f32_e32 v154, v188, v154
	v_mov_b32_e32 v188, v215
	v_add_f32_e32 v156, v154, v155
	v_pk_mul_f32 v[154:155], v[116:117], v[188:189]
	v_lshlrev_b32_e32 v185, 16, v185
	v_add_f32_e32 v154, v184, v154
	v_mov_b32_e32 v184, v213
	v_add_f32_e32 v204, v154, v155
	v_pk_mul_f32 v[154:155], v[138:139], v[184:185]
	v_and_b32_e32 v163, 0xffff0000, v181
	v_add_f32_e32 v154, v182, v154
	v_mov_b32_e32 v182, v211
	v_add_f32_e32 v205, v154, v155
	v_pk_mul_f32 v[154:155], v[114:115], v[182:183]
	v_lshlrev_b32_e32 v181, 16, v181
	v_add_f32_e32 v154, v180, v154
	v_mov_b32_e32 v180, v209
	v_add_f32_e32 v222, v154, v155
	v_pk_mul_f32 v[154:155], v[136:137], v[180:181]
	v_add_f32_e32 v218, v126, v218
	v_add_f32_e32 v154, v162, v154
	v_mov_b32_e32 v162, v187
	v_add_f32_e32 v223, v154, v155
	v_pk_mul_f32 v[154:155], v[112:113], v[162:163]
	v_pk_mul_f32 v[216:217], v[150:151], v[216:217]
	v_add_f32_e32 v154, v160, v154
	v_add_f32_e32 v154, v154, v155
	v_cvt_pk_bf16_f32 v154, v223, v154
	v_cvt_pk_bf16_f32 v155, v205, v222
	v_cvt_pk_bf16_f32 v156, v156, v204
	v_cvt_pk_bf16_f32 v157, v157, v161
	global_load_dwordx4 v[158:161], v[158:159], off
	v_add_f32_e32 v222, v218, v219
	v_pk_mul_f32 v[218:219], v[134:135], v[220:221]
	ds_write_b128 v199, v[154:157] offset:432
	v_add_f32_e32 v218, v127, v218
	v_add_f32_e32 v223, v218, v219
	v_mov_b32_e32 v218, v193
	v_mov_b32_e32 v220, v203
	v_add_f32_e32 v216, v124, v216
	v_pk_mul_f32 v[208:209], v[140:141], v[208:209]
	v_pk_mul_f32 v[186:187], v[120:121], v[186:187]
	v_add_f32_e32 v224, v216, v217
	v_pk_mul_f32 v[214:215], v[132:133], v[214:215]
	v_add_f32_e32 v208, v128, v208
	v_add_f32_e32 v186, v129, v186
	v_mov_b32_e32 v216, v191
	v_add_f32_e32 v214, v125, v214
	v_add_f32_e32 v228, v208, v209
	v_add_f32_e32 v229, v186, v187
	v_add_f32_e32 v225, v214, v215
	v_pk_mul_f32 v[212:213], v[142:143], v[212:213]
	v_mov_b32_e32 v214, v189
	v_add_f32_e32 v212, v130, v212
	v_pk_mul_f32 v[210:211], v[122:123], v[210:211]
	v_add_f32_e32 v226, v212, v213
	v_add_f32_e32 v210, v131, v210
	v_mov_b32_e32 v212, v185
	v_add_f32_e32 v227, v210, v211
	v_mov_b32_e32 v210, v183
	v_mov_b32_e32 v208, v181
	v_mov_b32_e32 v186, v163
	v_lshl_add_u64 v[204:205], v[144:145], 0, s[58:59]
	v_pk_mul_f32 v[192:193], v[152:153], v[192:193]
	v_pk_mul_f32 v[202:203], v[134:135], v[202:203]
	v_add_f32_e32 v192, v126, v192
	v_add_f32_e32 v202, v127, v202
	v_pk_mul_f32 v[190:191], v[150:151], v[190:191]
	v_pk_mul_f32 v[180:181], v[140:141], v[180:181]
	v_pk_mul_f32 v[162:163], v[120:121], v[162:163]
	v_add_f32_e32 v190, v124, v190
	v_pk_mul_f32 v[188:189], v[132:133], v[188:189]
	v_add_f32_e32 v180, v128, v180
	v_add_f32_e32 v162, v129, v162
	v_add_f32_e32 v188, v125, v188
	v_pk_mul_f32 v[184:185], v[142:143], v[184:185]
	v_pk_mul_f32 v[182:183], v[122:123], v[182:183]
	v_add_f32_e32 v184, v130, v184
	v_add_f32_e32 v182, v131, v182
	s_waitcnt vmcnt(0)
; #define LAS __attribute__((address_space(3)))
; __device__ __forceinline__ unsigned pk2(float lo, float hi) { return pg8::cvt_pk_bf16(lo, hi); }
; template <int PASS>
; __device__ __forceinline__ void lru_unit(const LruP& P, const LruInv& V, int b, int c, LAS unsigned char* wl, LAS float* red, int wave, int lane, int pairpos) {
;     ...
;         auto ldrow = [&](int ds, float* o) { const bool okr = (s0 + ds >= 0); v4u r = *(const v4u*)(src + (ptrdiff_t)(okr ? ds : 0) * NU); if (!okr) r = (v4u){0u, 0u, 0u, 0u};
;             o[0] = bflo(r.x); o[1] = bfhi(r.x); o[2] = bflo(r.y); o[3] = bfhi(r.y); o[4] = bflo(r.z); o[5] = bfhi(r.z); o[6] = bflo(r.w); o[7] = bfhi(r.w); };
;         ldrow(-3, w0); ldrow(-2, w1); ldrow(-1, w2);
; #pragma unroll
;         for (int t = 0; t < 8; ++t) { float cur[8], y[8]; ldrow(t, cur);
; #pragma unroll
;             for (int k = 0; k < 8; ++k) { y[k] = cb[k] + cw[0][k] * w0[k] + cw[1][k] * w1[k] + cw[2][k] * w2[k] + cw[3][k] * cur[k]; w0[k] = w1[k]; w1[k] = w2[k]; w2[k] = cur[k]; }
;             v4u o; o.x = pk2(y[0], y[1]); o.y = pk2(y[2], y[3]); o.z = pk2(y[4], y[5]); o.w = pk2(y[6], y[7]);
;             *(LAS v4u*)(xc + (tg * 8 + t) * 72 + cg8 * 8) = o; }
	v_cndmask_b32_e64 v161, 0, v161, s[4:5]
	v_lshlrev_b32_e32 v219, 16, v161
	v_pk_mul_f32 v[154:155], v[148:149], v[218:219]
	v_and_b32_e32 v221, 0xffff0000, v161
	v_add_f32_e32 v154, v222, v154
	v_cndmask_b32_e64 v160, 0, v160, s[4:5]
	v_add_f32_e32 v157, v154, v155
	v_pk_mul_f32 v[154:155], v[118:119], v[220:221]
	v_cndmask_b32_e64 v158, 0, v158, s[4:5]
	v_lshlrev_b32_e32 v217, 16, v160
	v_add_f32_e32 v154, v223, v154
	v_and_b32_e32 v187, 0xffff0000, v158
	v_lshlrev_b32_e32 v209, 16, v158
	v_add_f32_e32 v158, v154, v155
	v_pk_mul_f32 v[154:155], v[146:147], v[216:217]
	v_and_b32_e32 v215, 0xffff0000, v160
	v_add_f32_e32 v154, v224, v154
	v_cndmask_b32_e64 v159, 0, v159, s[4:5]
	v_add_f32_e32 v156, v154, v155
	v_pk_mul_f32 v[154:155], v[116:117], v[214:215]
	v_lshlrev_b32_e32 v213, 16, v159
	v_add_f32_e32 v154, v225, v154
	v_and_b32_e32 v211, 0xffff0000, v159
	v_add_f32_e32 v159, v154, v155
	v_pk_mul_f32 v[154:155], v[138:139], v[212:213]
	v_add_f32_e32 v223, v202, v203
	v_add_f32_e32 v154, v226, v154
	v_add_f32_e32 v160, v154, v155
	v_pk_mul_f32 v[154:155], v[114:115], v[210:211]
	v_mov_b32_e32 v202, v221
	v_add_f32_e32 v154, v227, v154
	v_add_f32_e32 v161, v154, v155
	v_pk_mul_f32 v[154:155], v[136:137], v[208:209]
	v_add_f32_e32 v224, v190, v191
	v_add_f32_e32 v154, v228, v154
	v_add_f32_e32 v222, v154, v155
	v_pk_mul_f32 v[154:155], v[112:113], v[186:187]
	v_mov_b32_e32 v190, v217
	v_add_f32_e32 v154, v229, v154
	v_add_f32_e32 v154, v154, v155
	v_cvt_pk_bf16_f32 v154, v222, v154
	v_cvt_pk_bf16_f32 v155, v160, v161
	v_cvt_pk_bf16_f32 v156, v156, v159
	v_cvt_pk_bf16_f32 v157, v157, v158
	global_load_dwordx4 v[158:161], v[204:205], off
	v_add_f32_e32 v222, v192, v193
	v_mov_b32_e32 v192, v219
	ds_write_b128 v199, v[154:157] offset:576
	v_add_f32_e32 v228, v180, v181
	v_add_f32_e32 v229, v162, v163
	v_add_f32_e32 v225, v188, v189
	v_mov_b32_e32 v188, v215
	v_add_f32_e32 v226, v184, v185
	v_mov_b32_e32 v184, v213
	v_add_f32_e32 v227, v182, v183
	v_mov_b32_e32 v182, v211
	v_mov_b32_e32 v180, v209
	v_mov_b32_e32 v162, v187
	v_lshl_add_u64 v[204:205], v[144:145], 0, s[56:57]
	v_pk_mul_f32 v[216:217], v[150:151], v[216:217]
	v_pk_mul_f32 v[214:215], v[132:133], v[214:215]
	v_pk_mul_f32 v[212:213], v[142:143], v[212:213]
	v_add_f32_e32 v216, v124, v216
	v_add_f32_e32 v214, v125, v214
	v_add_f32_e32 v212, v130, v212
	v_pk_mul_f32 v[186:187], v[120:121], v[186:187]
	v_pk_mul_f32 v[210:211], v[122:123], v[210:211]
	v_add_f32_e32 v186, v129, v186
	v_pk_mul_f32 v[208:209], v[140:141], v[208:209]
	v_add_f32_e32 v210, v131, v210
	v_add_f32_e32 v208, v128, v208
	v_lshl_add_u64 v[144:145], v[144:145], 0, s[44:45]
	s_waitcnt vmcnt(0)
	v_cndmask_b32_e64 v161, 0, v161, s[4:5]
	v_lshlrev_b32_e32 v193, 16, v161
	v_pk_mul_f32 v[154:155], v[148:149], v[192:193]
	v_and_b32_e32 v203, 0xffff0000, v161
	v_add_f32_e32 v154, v222, v154
	v_cndmask_b32_e64 v160, 0, v160, s[4:5]
	v_add_f32_e32 v157, v154, v155
	v_pk_mul_f32 v[154:155], v[118:119], v[202:203]
	v_cndmask_b32_e64 v158, 0, v158, s[4:5]
	v_lshlrev_b32_e32 v191, 16, v160
	v_add_f32_e32 v154, v223, v154
	v_and_b32_e32 v163, 0xffff0000, v158
	v_lshlrev_b32_e32 v181, 16, v158
	v_add_f32_e32 v158, v154, v155
	v_pk_mul_f32 v[154:155], v[146:147], v[190:191]
	v_and_b32_e32 v189, 0xffff0000, v160
	v_add_f32_e32 v154, v224, v154
	v_cndmask_b32_e64 v159, 0, v159, s[4:5]
	v_add_f32_e32 v156, v154, v155
	v_pk_mul_f32 v[154:155], v[116:117], v[188:189]
	v_lshlrev_b32_e32 v185, 16, v159
	v_add_f32_e32 v154, v225, v154
	v_and_b32_e32 v183, 0xffff0000, v159
	v_add_f32_e32 v159, v154, v155
	v_pk_mul_f32 v[154:155], v[138:139], v[184:185]
	v_add_f32_e32 v223, v212, v213
	v_add_f32_e32 v154, v226, v154
	v_add_f32_e32 v160, v154, v155
	v_pk_mul_f32 v[154:155], v[114:115], v[182:183]
	v_add_f32_e32 v226, v186, v187
	v_add_f32_e32 v154, v227, v154
	v_add_f32_e32 v161, v154, v155
	v_pk_mul_f32 v[154:155], v[136:137], v[180:181]
	v_mov_b32_e32 v212, v189
	v_add_f32_e32 v154, v228, v154
	v_add_f32_e32 v222, v154, v155
	v_pk_mul_f32 v[154:155], v[112:113], v[162:163]
	v_add_f32_e32 v224, v210, v211
	v_add_f32_e32 v154, v229, v154
	v_add_f32_e32 v154, v154, v155
	v_cvt_pk_bf16_f32 v154, v222, v154
	v_cvt_pk_bf16_f32 v155, v160, v161
	v_cvt_pk_bf16_f32 v156, v156, v159
	v_cvt_pk_bf16_f32 v157, v157, v158
	global_load_dwordx4 v[158:161], v[204:205], off
	v_pk_mul_f32 v[204:205], v[152:153], v[218:219]
	v_pk_mul_f32 v[218:219], v[134:135], v[220:221]
	ds_write_b128 v199, v[154:157] offset:720
	v_add_f32_e32 v204, v126, v204
	v_add_f32_e32 v218, v127, v218
	v_add_f32_e32 v221, v216, v217
	v_mov_b32_e32 v216, v193
	v_add_f32_e32 v204, v204, v205
	v_add_f32_e32 v220, v218, v219
	v_add_f32_e32 v222, v214, v215
	v_mov_b32_e32 v218, v203
	v_mov_b32_e32 v214, v191
	v_add_f32_e32 v225, v208, v209
	v_mov_b32_e32 v210, v185
	v_mov_b32_e32 v208, v183
	v_mov_b32_e32 v186, v163
	v_pk_mul_f32 v[122:123], v[122:123], v[182:183]
	v_pk_mul_f32 v[120:121], v[120:121], v[162:163]
	v_pk_mul_f32 v[140:141], v[140:141], v[180:181]
	v_pk_mul_f32 v[134:135], v[134:135], v[202:203]
	v_add_f32_e32 v122, v131, v122
	v_pk_mul_f32 v[142:143], v[142:143], v[184:185]
	v_pk_mul_f32 v[132:133], v[132:133], v[188:189]
	v_add_f32_e32 v120, v129, v120
	v_add_f32_e32 v128, v128, v140
	v_add_f32_e32 v127, v127, v134
	v_add_f32_e32 v140, v122, v123
	v_add_f32_e32 v129, v130, v142
	v_add_f32_e32 v125, v125, v132
	v_add_f32_e32 v132, v120, v121
	v_add_f32_e32 v135, v127, v135
	v_add_f32_e32 v130, v128, v141
	v_add_f32_e32 v134, v129, v143
	v_add_f32_e32 v133, v125, v133
	v_mov_b32_e32 v180, 0
	v_mov_b32_e32 v182, 0
	v_mov_b32_e32 v183, 0
	s_waitcnt vmcnt(0)
; #define LAS __attribute__((address_space(3)))
; #define LDS_WAIT() asm volatile("s_waitcnt lgkmcnt(0)" ::: "memory")
; __device__ __forceinline__ unsigned pk2(float lo, float hi) { return pg8::cvt_pk_bf16(lo, hi); }
; template <int PASS>
; __device__ __forceinline__ void lru_unit(const LruP& P, const LruInv& V, int b, int c, LAS unsigned char* wl, LAS float* red, int wave, int lane, int pairpos) {
;     ...
;         for (int t = 0; t < 8; ++t) { float cur[8], y[8]; ldrow(t, cur);
; #pragma unroll
;             for (int k = 0; k < 8; ++k) { y[k] = cb[k] + cw[0][k] * w0[k] + cw[1][k] * w1[k] + cw[2][k] * w2[k] + cw[3][k] * cur[k]; w0[k] = w1[k]; w1[k] = w2[k]; w2[k] = cur[k]; }
;             v4u o; o.x = pk2(y[0], y[1]); o.y = pk2(y[2], y[3]); o.z = pk2(y[4], y[5]); o.w = pk2(y[6], y[7]);
;             *(LAS v4u*)(xc + (tg * 8 + t) * 72 + cg8 * 8) = o; }
;     }
;     LDS_WAIT(); __builtin_amdgcn_wave_barrier();
;     float hin[4][4], arun[4][4];
;     LAS float* stash = (LAS float*)(wl + 9216) + fq * 32;
; #pragma unroll
;     for (int n = 0; n < 4; ++n)
; #pragma unroll
;         for (int j = 0; j < 4; ++j) { hin[n][j] = (pairpos == 1) ? stash[(n * 4 + j) * 2] : 0.f; arun[n][j] = (pairpos == 1) ? stash[(n * 4 + j) * 2 + 1] : 1.f; }
	v_cndmask_b32_e64 v154, 0, v161, s[4:5]
	v_cndmask_b32_e64 v155, 0, v160, s[4:5]
	v_lshlrev_b32_e32 v217, 16, v154
	v_and_b32_e32 v213, 0xffff0000, v155
	v_lshlrev_b32_e32 v215, 16, v155
	v_and_b32_e32 v219, 0xffff0000, v154
	v_pk_mul_f32 v[154:155], v[148:149], v[216:217]
	v_cndmask_b32_e64 v157, 0, v158, s[4:5]
	v_add_f32_e32 v154, v204, v154
	v_and_b32_e32 v187, 0xffff0000, v157
	v_lshlrev_b32_e32 v205, 16, v157
	v_add_f32_e32 v157, v154, v155
	v_pk_mul_f32 v[154:155], v[118:119], v[218:219]
	v_cndmask_b32_e64 v156, 0, v159, s[4:5]
	v_add_f32_e32 v154, v220, v154
	v_add_f32_e32 v158, v154, v155
	v_pk_mul_f32 v[154:155], v[146:147], v[214:215]
	v_and_b32_e32 v209, 0xffff0000, v156
	v_add_f32_e32 v154, v221, v154
	v_lshlrev_b32_e32 v211, 16, v156
	v_add_f32_e32 v156, v154, v155
	v_pk_mul_f32 v[154:155], v[116:117], v[212:213]
	v_mov_b32_e32 v204, v181
	v_add_f32_e32 v154, v222, v154
	v_add_f32_e32 v159, v154, v155
	v_pk_mul_f32 v[154:155], v[138:139], v[210:211]
	v_mov_b32_e32 v120, v187
	v_add_f32_e32 v154, v223, v154
	v_add_f32_e32 v160, v154, v155
	v_pk_mul_f32 v[154:155], v[114:115], v[208:209]
	v_mov_b32_e32 v122, v205
	v_add_f32_e32 v154, v224, v154
	v_add_f32_e32 v161, v154, v155
	v_pk_mul_f32 v[154:155], v[136:137], v[204:205]
	v_mov_b32_e32 v128, v213
	v_add_f32_e32 v154, v225, v154
	v_add_f32_e32 v204, v154, v155
	v_pk_mul_f32 v[154:155], v[112:113], v[186:187]
	v_mov_b32_e32 v181, 0
	v_add_f32_e32 v154, v226, v154
	v_add_f32_e32 v154, v154, v155
	v_cvt_pk_bf16_f32 v154, v204, v154
	v_cvt_pk_bf16_f32 v155, v160, v161
	v_cvt_pk_bf16_f32 v156, v156, v159
	v_cvt_pk_bf16_f32 v157, v157, v158
	global_load_dwordx4 v[158:161], v[144:145], off
	v_pk_mul_f32 v[144:145], v[150:151], v[190:191]
	v_pk_mul_f32 v[150:151], v[152:153], v[192:193]
	v_add_f32_e32 v124, v124, v144
	v_add_f32_e32 v126, v126, v150
	v_add_f32_e32 v142, v126, v151
	v_mov_b32_e32 v126, v211
	v_add_f32_e32 v141, v124, v145
	v_mov_b32_e32 v124, v209
	ds_write_b128 v199, v[154:157] offset:864
	v_mov_b32_e32 v152, 0
	v_mov_b32_e32 v144, 0
	v_mov_b32_e32 v145, 1.0
	v_mov_b32_e32 v153, 1.0
	v_mov_b32_e32 v157, 1.0
	s_waitcnt vmcnt(0)
	v_cndmask_b32_e64 v123, 0, v158, s[4:5]
	v_cndmask_b32_e64 v127, 0, v159, s[4:5]
	v_and_b32_e32 v121, 0xffff0000, v123
	v_lshlrev_b32_e32 v123, 16, v123
	v_cndmask_b32_e64 v143, 0, v161, s[4:5]
	v_cndmask_b32_e64 v131, 0, v160, s[4:5]
	v_and_b32_e32 v125, 0xffff0000, v127
	v_lshlrev_b32_e32 v127, 16, v127
	v_pk_mul_f32 v[112:113], v[112:113], v[120:121]
	v_pk_mul_f32 v[120:121], v[136:137], v[122:123]
	v_and_b32_e32 v129, 0xffff0000, v131
	v_pk_mul_f32 v[122:123], v[138:139], v[126:127]
	v_add_f32_e32 v112, v132, v112
	v_add_f32_e32 v120, v130, v120
	v_lshlrev_b32_e32 v127, 16, v143
	v_mov_b32_e32 v126, v217
	v_lshlrev_b32_e32 v131, 16, v131
	v_pk_mul_f32 v[116:117], v[116:117], v[128:129]
	v_mov_b32_e32 v130, v215
	v_add_f32_e32 v120, v120, v121
	v_add_f32_e32 v121, v112, v113
	v_pk_mul_f32 v[112:113], v[148:149], v[126:127]
	v_pk_mul_f32 v[114:115], v[114:115], v[124:125]
	v_add_f32_e32 v116, v133, v116
	v_pk_mul_f32 v[124:125], v[146:147], v[130:131]
	v_and_b32_e32 v129, 0xffff0000, v143
	v_add_f32_e32 v112, v142, v112
	v_mov_b32_e32 v128, v219
	v_add_f32_e32 v114, v140, v114
	v_add_f32_e32 v124, v141, v124
	v_add_f32_e32 v116, v116, v117
	v_add_f32_e32 v117, v112, v113
	v_pk_mul_f32 v[112:113], v[118:119], v[128:129]
	v_add_f32_e32 v122, v134, v122
	v_add_f32_e32 v114, v114, v115
	v_add_f32_e32 v115, v124, v125
	v_add_f32_e32 v112, v135, v112
	v_add_f32_e32 v122, v122, v123
	v_add_f32_e32 v118, v112, v113
	v_cvt_pk_bf16_f32 v112, v120, v121
	v_cvt_pk_bf16_f32 v113, v122, v114
	v_cvt_pk_bf16_f32 v114, v115, v116
	v_cvt_pk_bf16_f32 v115, v117, v118
	ds_write_b128 v200, v[112:115]
	s_waitcnt lgkmcnt(0)
	v_lshl_add_u64 v[114:115], v[172:173], 0, s[16:17]
	v_mov_b32_e32 v119, 1.0
	v_mov_b32_e32 v120, 0
	v_mov_b32_e32 v112, 0
	v_mov_b32_e32 v118, 0
	v_mov_b32_e32 v128, 0
	v_mov_b32_e32 v124, 0
	v_mov_b32_e32 v132, 0
	v_mov_b32_e32 v140, 0
	v_mov_b32_e32 v136, 0
	v_mov_b32_e32 v134, 0
	v_mov_b32_e32 v148, 0
	v_mov_b32_e32 v121, 1.0
	v_mov_b32_e32 v117, 1.0
	v_mov_b32_e32 v113, 1.0
	v_mov_b32_e32 v135, 1.0
	v_mov_b32_e32 v129, 1.0
	v_mov_b32_e32 v133, 1.0
	v_mov_b32_e32 v125, 1.0
	v_mov_b32_e32 v147, 1.0
	v_mov_b32_e32 v141, 1.0
	v_mov_b32_e32 v137, 1.0
	v_mov_b32_e32 v159, 1.0
	v_mov_b32_e32 v149, 1.0
